# skinny residual units: second row's XB value requested together with the first row's (one exposed round trip less in P3/P5/P10/P12)
# baseline (speedup 1.0000x reference)
; #define LAS __attribute__((address_space(3)))
; __device__ __forceinline__ float bf1(bf16 b) { return __uint_as_float((unsigned)b << 16); }
; template <bool FIRST> __device__ __forceinline__ void skinny_resid(const bf16* __restrict__ A, const bf16* __restrict__ Bt, int K, const float* xs, bf16* XB, float* SS, int u, LAS unsigned char* lds, int tid) {
;     ...
;     const int lane = tid & 63, w = __builtin_amdgcn_readfirstlane(tid >> 6), r16 = lane & 15, kq = lane >> 4, rt = u & 7, cu = u >> 3;
;     const bf16* ap = A + (size_t)(NP + 16 * rt + r16) * K + 8 * kq + 32 * w;
;     const bf16* bp = Bt + (size_t)(64 * cu + r16) * K + 8 * kq + 32 * w;
;     f32x4v acc[4];
; #pragma unroll
;     for (int ct = 0; ct < 4; ++ct) acc[ct] = (f32x4v){0.f, 0.f, 0.f, 0.f};
;     const int nj = K / 256;
; #pragma unroll 1
;     for (int j0 = 0; j0 < nj; j0 += 4) { bf16x8 af[4], bf[4][4];
; #pragma unroll
;         for (int s = 0; s < 4; ++s) { const int j = (j0 + s < nj) ? j0 + s : nj - 1;
;             af[s] = *(const bf16x8*)(ap + 256 * j);
; #pragma unroll
;             for (int ct = 0; ct < 4; ++ct) bf[s][ct] = *(const bf16x8*)(bp + (size_t)16 * ct * K + 256 * j); }
;         __builtin_amdgcn_sched_barrier(0);
; #pragma unroll
;         for (int s = 0; s < 4; ++s) if (j0 + s < nj) {
; #pragma unroll
;             for (int ct = 0; ct < 4; ++ct) acc[ct] = __builtin_amdgcn_mfma_f32_16x16x32_bf16(af[s], bf[s][ct], acc[ct], 0, 0, 0); }
;         __builtin_amdgcn_sched_barrier(0); }
;     LAS float* red = (LAS float*)(lds + SK_RED);
; #pragma unroll
;     for (int ct = 0; ct < 4; ++ct) *(LAS f32x4v*)(red + ((w * 4 + ct) * 64 + lane) * 4) = acc[ct];
;     __syncthreads();
; #pragma unroll
;     for (int rr = 0; rr < 2; ++rr) { const int lr = 2 * w + rr;
;         const int ct = lane >> 4, src_lane = (lr >> 2) * 16 + (lane & 15), reg = lr & 3;
;         float s = 0.f;
; #pragma unroll
;         for (int ww = 0; ww < 8; ++ww) s += red[((ww * 4 + ct) * 64 + src_lane) * 4 + reg];
;         const int srow = 16 * rt + lr; const size_t row = (size_t)NP + srow; const int col = 64 * cu + lane;
;         const float x = (FIRST ? xs[(size_t)srow * D + col] : bf1(XB[row * D + col])) + s;
;         XB[row * D + col] = (bf16)(pk2(x, 0.f) & 0xffffu);
;         const float sq = wave_sum(x * x);
;         if (lane == 0) SS[row * 16 + cu] = sq; }
.LBB0_715:
	v_mov_b32_e32 v86, v5
	s_ashr_i32 s4, s30, 3
	v_readfirstlane_b32 s5, v86
	v_and_b32_e32 v87, 15, v86
	s_and_b32 s35, s2, 0x70
	s_ashr_i32 s37, s5, 6
	v_or_b32_e32 v6, s35, v87
	s_lshl_b32 s31, s4, 6
	s_lshl_b32 s6, s37, 5
	v_or_b32_e32 v2, s31, v87
	v_lshlrev_b32_e32 v6, 11, v6
	v_mov_b32_e32 v7, v1
	s_ashr_i32 s7, s6, 31
	v_ashrrev_i32_e32 v3, 31, v2
	v_and_b32_e32 v0, 48, v86
	v_lshl_add_u64 v[6:7], s[22:23], 0, v[6:7]
	v_lshlrev_b64 v[2:3], 11, v[2:3]
	v_lshl_add_u64 v[6:7], v[6:7], 0, v[0:1]
	s_lshl_b64 s[6:7], s[6:7], 1
	v_lshl_add_u64 v[2:3], s[8:9], 0, v[2:3]
	v_lshl_add_u64 v[6:7], v[6:7], 0, s[6:7]
	v_lshl_add_u64 v[2:3], v[2:3], 0, v[0:1]
	s_waitcnt vmcnt(26)
	v_add_co_u32_e32 v54, vcc, s26, v6
	v_lshl_add_u64 v[2:3], v[2:3], 0, s[6:7]
	s_nop 0
	v_addc_co_u32_e32 v55, vcc, 0, v7, vcc
	v_add_co_u32_e32 v66, vcc, s27, v2
	s_waitcnt vmcnt(24)
	v_lshl_add_u64 v[50:51], v[6:7], 0, s[0:1]
	v_addc_co_u32_e32 v67, vcc, 0, v3, vcc
	v_add_co_u32_e32 v74, vcc, s28, v2
	v_and_b32_e32 v88, 63, v86
	s_nop 0
	v_addc_co_u32_e32 v75, vcc, 0, v3, vcc
	v_add_co_u32_e32 v82, vcc, s29, v2
	s_nop 1
	v_addc_co_u32_e32 v83, vcc, 0, v3, vcc
	global_load_dwordx4 v[6:9], v[66:67], off
	global_load_dwordx4 v[10:13], v[66:67], off offset:512
	global_load_dwordx4 v[14:17], v[74:75], off
	global_load_dwordx4 v[18:21], v[74:75], off offset:512
	global_load_dwordx4 v[22:25], v[82:83], off
	global_load_dwordx4 v[26:29], v[82:83], off offset:512
	global_load_dwordx4 v[30:33], v[50:51], off offset:512
	global_load_dwordx4 v[34:37], v[50:51], off offset:1024
	global_load_dwordx4 v[38:41], v[2:3], off offset:512
	global_load_dwordx4 v[42:45], v[2:3], off offset:1024
	global_load_dwordx4 v[46:49], v[2:3], off
	s_nop 0
	global_load_dwordx4 v[50:53], v[50:51], off offset:1536
	s_nop 0
	global_load_dwordx4 v[54:57], v[54:55], off
	s_nop 0
	global_load_dwordx4 v[58:61], v[2:3], off offset:1536
	global_load_dwordx4 v[62:65], v[66:67], off offset:1024
	s_nop 0
	global_load_dwordx4 v[66:69], v[66:67], off offset:1536
	s_nop 0
	global_load_dwordx4 v[70:73], v[74:75], off offset:1024
	s_nop 0
	global_load_dwordx4 v[74:77], v[74:75], off offset:1536
	s_nop 0
	global_load_dwordx4 v[78:81], v[82:83], off offset:1024
	s_nop 0
	global_load_dwordx4 v[82:85], v[82:83], off offset:1536
	s_waitcnt vmcnt(7)
	v_mfma_f32_16x16x32_bf16 v[6:9], v[54:57], v[6:9], 0
	v_mfma_f32_16x16x32_bf16 v[46:49], v[54:57], v[46:49], 0
	v_mfma_f32_16x16x32_bf16 v[14:17], v[54:57], v[14:17], 0
	v_mfma_f32_16x16x32_bf16 v[22:25], v[54:57], v[22:25], 0
	v_mfma_f32_16x16x32_bf16 v[6:9], v[30:33], v[10:13], v[6:9]
	v_mfma_f32_16x16x32_bf16 v[38:41], v[30:33], v[38:41], v[46:49]
	v_mfma_f32_16x16x32_bf16 v[10:13], v[30:33], v[18:21], v[14:17]
	v_mfma_f32_16x16x32_bf16 v[14:17], v[30:33], v[26:29], v[22:25]
	s_waitcnt vmcnt(5)
	v_mfma_f32_16x16x32_bf16 v[6:9], v[34:37], v[62:65], v[6:9]
	v_mfma_f32_16x16x32_bf16 v[18:21], v[34:37], v[42:45], v[38:41]
	s_waitcnt vmcnt(3)
	v_mfma_f32_16x16x32_bf16 v[10:13], v[34:37], v[70:73], v[10:13]
	s_waitcnt vmcnt(1)
	v_mfma_f32_16x16x32_bf16 v[14:17], v[34:37], v[78:81], v[14:17]
	v_mfma_f32_16x16x32_bf16 v[6:9], v[50:53], v[66:69], v[6:9]
	v_mfma_f32_16x16x32_bf16 v[18:21], v[50:53], v[58:61], v[18:21]
	v_mfma_f32_16x16x32_bf16 v[10:13], v[50:53], v[74:77], v[10:13]
	s_waitcnt vmcnt(0)
	v_mfma_f32_16x16x32_bf16 v[14:17], v[50:53], v[82:85], v[14:17]
	s_lshr_b32 s5, s5, 3
	s_lshl_b32 s6, s37, 12
	s_and_b32 s38, s5, 0xffffff0
	s_ashr_i32 s5, s4, 31
	s_add_i32 s6, s6, 0
	s_lshl_b32 s36, s37, 1
	s_bitset1_b32 s35, 14
	s_lshl_b64 s[4:5], s[4:5], 2
	v_or_b32_e32 v2, s31, v88
	s_add_u32 s31, s16, s4
	s_addc_u32 s34, s17, s5
	s_add_i32 s4, s36, s35
	v_ashrrev_i32_e32 v3, 31, v2
	s_ashr_i32 s5, s4, 31
	v_lshl_add_u32 v0, v88, 4, s6
	v_lshl_add_u64 v[2:3], v[2:3], 1, s[20:21]
	s_lshl_b64 s[6:7], s[4:5], 11
	ds_write_b128 v0, v[18:21]
	ds_write_b128 v0, v[6:9] offset:1024
	ds_write_b128 v0, v[10:13] offset:2048
	ds_write_b128 v0, v[14:17] offset:3072
	v_lshl_add_u64 v[8:9], v[2:3], 0, s[6:7]
	s_waitcnt lgkmcnt(0)
	s_barrier
	global_load_ushort v7, v[8:9], off
	s_or_b32 s98, s36, 1
	s_add_i32 s98, s98, s35
	s_ashr_i32 s99, s98, 31
	s_lshl_b64 s[98:99], s[98:99], 11
	v_lshl_add_u64 v[240:241], v[2:3], 0, s[98:99]
	global_load_ushort v242, v[240:241], off
	s_lshl_b32 s6, s37, 3
	v_lshlrev_b32_e32 v0, 6, v86
	v_or_b32_e32 v6, s38, v87
	s_and_b32 s6, s6, 8
	v_and_b32_e32 v0, 0xc00, v0
	v_lshlrev_b32_e32 v6, 4, v6
	s_add_i32 s6, s6, 0
	v_add3_u32 v16, s6, v0, v6
	ds_read2st64_b32 v[10:11], v16 offset1:16
	ds_read2st64_b32 v[12:13], v16 offset0:32 offset1:48
	ds_read2st64_b32 v[14:15], v16 offset0:64 offset1:80
	ds_read2st64_b32 v[16:17], v16 offset0:96 offset1:112
	v_cmp_eq_u32_e32 vcc, 0, v88
	s_waitcnt lgkmcnt(3)
	v_add_f32_e32 v10, 0, v10
	v_add_f32_e32 v10, v10, v11
	s_waitcnt lgkmcnt(2)
	v_add_f32_e32 v10, v10, v12
	v_add_f32_e32 v10, v10, v13
	s_waitcnt lgkmcnt(1)
	v_add_f32_e32 v10, v10, v14
	v_add_f32_e32 v10, v10, v15
	s_waitcnt lgkmcnt(0)
	v_add_f32_e32 v10, v10, v16
	v_add_f32_e32 v10, v10, v17
	s_waitcnt vmcnt(0)
	v_lshlrev_b32_e32 v7, 16, v7
	v_add_f32_e32 v7, v10, v7
	v_mul_f32_e32 v10, v7, v7
	s_nop 1
	v_mov_b32_dpp v10, v10 quad_perm:[1,0,3,2] row_mask:0xf bank_mask:0xf bound_ctrl:1
	v_fmac_f32_e32 v10, v7, v7
	v_cvt_pk_bf16_f32 v7, v7, s0
	global_store_short v[8:9], v7, off
	v_add_f32_dpp v10, v10, v10 quad_perm:[2,3,0,1] row_mask:0xf bank_mask:0xf bound_ctrl:1
	s_nop 1
	v_add_f32_dpp v10, v10, v10 row_half_mirror row_mask:0xf bank_mask:0xf bound_ctrl:1
	s_nop 1
	v_add_f32_dpp v10, v10, v10 row_mirror row_mask:0xf bank_mask:0xf bound_ctrl:1
	ds_swizzle_b32 v11, v10 offset:swizzle(SWAP,16)
	s_waitcnt lgkmcnt(0)
	v_add_f32_e32 v7, v10, v11
	v_mov_b32_e32 v8, v7
	s_nop 1
	v_permlane32_swap_b32_e32 v7, v8
	s_and_saveexec_b64 s[6:7], vcc
	s_cbranch_execz .LBB0_717
	s_lshl_b64 s[4:5], s[4:5], 6
	s_add_u32 s4, s31, s4
	v_add_f32_e32 v7, v7, v8
	s_addc_u32 s5, s34, s5
	global_store_dword v1, v7, s[4:5]
; __device__ __forceinline__ unsigned pk2(float lo, float hi) { f32x2_t v = {lo, hi}; bf16x2_t b = __builtin_convertvector(v, bf16x2_t); return __builtin_bit_cast(unsigned, b); }
; __device__ __forceinline__ float bf1(bf16 b) { return __uint_as_float((unsigned)b << 16); }
; __device__ __forceinline__ float wave_sum(float v) { v = sum16(v); v += lane_xor<16>(v); return xhalf_sum(v); }
; template <bool FIRST> __device__ __forceinline__ void skinny_resid(const bf16* __restrict__ A, const bf16* __restrict__ Bt, int K, const float* xs, bf16* XB, float* SS, int u, LAS unsigned char* lds, int tid) {
;     ...
;     for (int rr = 0; rr < 2; ++rr) { const int lr = 2 * w + rr;
;         const int ct = lane >> 4, src_lane = (lr >> 2) * 16 + (lane & 15), reg = lr & 3;
;         float s = 0.f;
; #pragma unroll
;         for (int ww = 0; ww < 8; ++ww) s += red[((ww * 4 + ct) * 64 + src_lane) * 4 + reg];
;         const int srow = 16 * rt + lr; const size_t row = (size_t)NP + srow; const int col = 64 * cu + lane;
;         const float x = (FIRST ? xs[(size_t)srow * D + col] : bf1(XB[row * D + col])) + s;
;         XB[row * D + col] = (bf16)(pk2(x, 0.f) & 0xffffu);
;         const float sq = wave_sum(x * x);
;         if (lane == 0) SS[row * 16 + cu] = sq; }
.LBB0_717:
	s_or_b64 exec, exec, s[6:7]
	s_or_b32 s36, s36, 1
	s_add_i32 s4, s36, s35
	s_ashr_i32 s5, s4, 31
	s_lshl_b64 s[6:7], s[4:5], 11
	v_lshl_add_u64 v[2:3], v[2:3], 0, s[6:7]
	v_mov_b32_e32 v14, v242
	s_and_b32 s6, s36, 3
	s_lshl_b32 s6, s6, 2
	s_add_i32 s6, s6, 0
	v_add3_u32 v0, s6, v0, v6
	ds_read2st64_b32 v[6:7], v0 offset1:16
	ds_read2st64_b32 v[8:9], v0 offset0:32 offset1:48
	ds_read2st64_b32 v[10:11], v0 offset0:64 offset1:80
	ds_read2st64_b32 v[12:13], v0 offset0:96 offset1:112
	s_waitcnt lgkmcnt(3)
	v_add_f32_e32 v0, 0, v6
	v_add_f32_e32 v0, v0, v7
	s_waitcnt lgkmcnt(2)
	v_add_f32_e32 v0, v0, v8
	v_add_f32_e32 v0, v0, v9
	s_waitcnt lgkmcnt(1)
	v_add_f32_e32 v0, v0, v10
	v_add_f32_e32 v0, v0, v11
	s_waitcnt lgkmcnt(0)
	v_add_f32_e32 v0, v0, v12
	v_add_f32_e32 v0, v0, v13
	s_waitcnt vmcnt(0)
	v_lshlrev_b32_e32 v6, 16, v14
	v_add_f32_e32 v0, v0, v6
	v_mul_f32_e32 v6, v0, v0
	s_nop 1
	v_mov_b32_dpp v6, v6 quad_perm:[1,0,3,2] row_mask:0xf bank_mask:0xf bound_ctrl:1
	v_fmac_f32_e32 v6, v0, v0
	v_cvt_pk_bf16_f32 v0, v0, s0
	global_store_short v[2:3], v0, off
	v_add_f32_dpp v6, v6, v6 quad_perm:[2,3,0,1] row_mask:0xf bank_mask:0xf bound_ctrl:1
	s_nop 1
	v_add_f32_dpp v6, v6, v6 row_half_mirror row_mask:0xf bank_mask:0xf bound_ctrl:1
	s_nop 1
	v_add_f32_dpp v6, v6, v6 row_mirror row_mask:0xf bank_mask:0xf bound_ctrl:1
	ds_swizzle_b32 v7, v6 offset:swizzle(SWAP,16)
	s_waitcnt lgkmcnt(0)
	v_add_f32_e32 v0, v6, v7
	v_mov_b32_e32 v2, v0
	s_nop 1
	v_permlane32_swap_b32_e32 v0, v2
	s_and_saveexec_b64 s[6:7], vcc
	s_cbranch_execz .LBB0_714
	s_lshl_b64 s[4:5], s[4:5], 6
	s_add_u32 s4, s31, s4
	v_add_f32_e32 v0, v0, v2
	s_addc_u32 s5, s34, s5
	global_store_dword v1, v0, s[4:5]
	s_branch .LBB0_714

; #define LAS __attribute__((address_space(3)))
; __device__ __forceinline__ unsigned pk2(float lo, float hi) { f32x2_t v = {lo, hi}; bf16x2_t b = __builtin_convertvector(v, bf16x2_t); return __builtin_bit_cast(unsigned, b); }
; __device__ __forceinline__ float bf1(bf16 b) { return __uint_as_float((unsigned)b << 16); }
; __device__ __forceinline__ float wave_sum(float v) { v = sum16(v); v += lane_xor<16>(v); return xhalf_sum(v); }
; template <bool FIRST> __device__ __forceinline__ void skinny_resid(const bf16* __restrict__ A, const bf16* __restrict__ Bt, int K, const float* xs, bf16* XB, float* SS, int u, LAS unsigned char* lds, int tid) {
;     ...
;     LAS float* red = (LAS float*)(lds + SK_RED);
; #pragma unroll
;     for (int ct = 0; ct < 4; ++ct) *(LAS f32x4v*)(red + ((w * 4 + ct) * 64 + lane) * 4) = acc[ct];
;     __syncthreads();
; #pragma unroll
;     for (int rr = 0; rr < 2; ++rr) { const int lr = 2 * w + rr;
;         const int ct = lane >> 4, src_lane = (lr >> 2) * 16 + (lane & 15), reg = lr & 3;
;         float s = 0.f;
; #pragma unroll
;         for (int ww = 0; ww < 8; ++ww) s += red[((ww * 4 + ct) * 64 + src_lane) * 4 + reg];
;         const int srow = 16 * rt + lr; const size_t row = (size_t)NP + srow; const int col = 64 * cu + lane;
;         const float x = (FIRST ? xs[(size_t)srow * D + col] : bf1(XB[row * D + col])) + s;
;         XB[row * D + col] = (bf16)(pk2(x, 0.f) & 0xffffu);
;         const float sq = wave_sum(x * x);
;         if (lane == 0) SS[row * 16 + cu] = sq; }
.LBB0_1312:
	s_lshr_b32 s1, s1, 3
	s_lshl_b32 s18, s37, 12
	s_and_b32 s44, s1, 0xffffff0
	s_ashr_i32 s1, s0, 31
	s_add_i32 s18, s18, 0
	s_lshl_b32 s41, s37, 1
	s_or_b32 s40, s38, 0x4000
	s_lshl_b64 s[0:1], s[0:1], 2
	v_lshl_add_u32 v18, v32, 4, s18
	s_add_u32 s18, s22, s0
	ds_write_b128 v18, v[12:15]
	ds_write_b128 v18, v[8:11] offset:1024
	ds_write_b128 v18, v[4:7] offset:2048
	ds_write_b128 v18, v[0:3] offset:3072
	v_or_b32_e32 v0, s39, v32
	s_addc_u32 s38, s23, s1
	s_add_i32 s0, s41, s40
	v_ashrrev_i32_e32 v1, 31, v0
	s_ashr_i32 s1, s0, 31
	v_lshl_add_u64 v[0:1], v[0:1], 1, s[24:25]
	s_lshl_b64 s[42:43], s[0:1], 11
	v_lshl_add_u64 v[4:5], v[0:1], 0, s[42:43]
	s_waitcnt lgkmcnt(0)
	s_barrier
	global_load_ushort v14, v[4:5], off
	s_or_b32 s98, s41, 1
	s_add_i32 s98, s98, s40
	s_ashr_i32 s99, s98, 31
	s_lshl_b64 s[98:99], s[98:99], 11
	v_lshl_add_u64 v[240:241], v[0:1], 0, s[98:99]
	global_load_ushort v242, v[240:241], off
	s_lshl_b32 s37, s37, 3
	v_or_b32_e32 v3, s44, v33
	s_and_b32 s37, s37, 8
	v_lshlrev_b32_e32 v2, 10, v34
	v_lshlrev_b32_e32 v3, 4, v3
	s_add_i32 s37, s37, 0
	v_add3_u32 v12, s37, v2, v3
	ds_read2st64_b32 v[6:7], v12 offset1:16
	ds_read2st64_b32 v[8:9], v12 offset0:32 offset1:48
	ds_read2st64_b32 v[10:11], v12 offset0:64 offset1:80
	ds_read2st64_b32 v[12:13], v12 offset0:96 offset1:112
	v_cmp_eq_u32_e32 vcc, 0, v32
	s_waitcnt lgkmcnt(3)
	v_add_f32_e32 v6, 0, v6
	v_add_f32_e32 v6, v6, v7
	s_waitcnt lgkmcnt(2)
	v_add_f32_e32 v6, v6, v8
	v_add_f32_e32 v6, v6, v9
	s_waitcnt lgkmcnt(1)
	v_add_f32_e32 v6, v6, v10
	v_add_f32_e32 v6, v6, v11
	s_waitcnt lgkmcnt(0)
	v_add_f32_e32 v6, v6, v12
	v_add_f32_e32 v6, v6, v13
	s_waitcnt vmcnt(0)
	v_lshlrev_b32_e32 v7, 16, v14
	v_add_f32_e32 v6, v6, v7
	v_mul_f32_e32 v7, v6, v6
	s_nop 1
	v_mov_b32_dpp v7, v7 quad_perm:[1,0,3,2] row_mask:0xf bank_mask:0xf bound_ctrl:1
	v_fmac_f32_e32 v7, v6, v6
	v_cvt_pk_bf16_f32 v6, v6, s0
	global_store_short v[4:5], v6, off
	v_add_f32_dpp v7, v7, v7 quad_perm:[2,3,0,1] row_mask:0xf bank_mask:0xf bound_ctrl:1
	s_nop 1
	v_add_f32_dpp v7, v7, v7 row_half_mirror row_mask:0xf bank_mask:0xf bound_ctrl:1
	s_nop 1
	v_add_f32_dpp v7, v7, v7 row_mirror row_mask:0xf bank_mask:0xf bound_ctrl:1
	ds_swizzle_b32 v8, v7 offset:swizzle(SWAP,16)
	s_waitcnt lgkmcnt(0)
	v_add_f32_e32 v4, v7, v8
	v_mov_b32_e32 v5, v4
	s_nop 1
	v_permlane32_swap_b32_e32 v4, v5
	s_and_saveexec_b64 s[42:43], vcc
	s_cbranch_execz .LBB0_1314
	s_lshl_b64 s[0:1], s[0:1], 6
	s_add_u32 s0, s18, s0
	v_add_f32_e32 v4, v4, v5
	s_addc_u32 s1, s38, s1
	global_store_dword v19, v4, s[0:1]
.LBB0_1314:
	s_or_b64 exec, exec, s[42:43]
	s_or_b32 s37, s41, 1
	s_add_i32 s0, s37, s40
	s_ashr_i32 s1, s0, 31
	s_lshl_b64 s[40:41], s[0:1], 11
	v_lshl_add_u64 v[0:1], v[0:1], 0, s[40:41]
	v_mov_b32_e32 v10, v242
	s_and_b32 s37, s37, 3
	s_lshl_b32 s37, s37, 2
	s_add_i32 s37, s37, 0
	v_add3_u32 v8, s37, v2, v3
	ds_read2st64_b32 v[2:3], v8 offset1:16
	ds_read2st64_b32 v[4:5], v8 offset0:32 offset1:48
	ds_read2st64_b32 v[6:7], v8 offset0:64 offset1:80
	ds_read2st64_b32 v[8:9], v8 offset0:96 offset1:112
	s_waitcnt lgkmcnt(3)
	v_add_f32_e32 v2, 0, v2
	v_add_f32_e32 v2, v2, v3
	s_waitcnt lgkmcnt(2)
	v_add_f32_e32 v2, v2, v4
	v_add_f32_e32 v2, v2, v5
	s_waitcnt lgkmcnt(1)
	v_add_f32_e32 v2, v2, v6
	v_add_f32_e32 v2, v2, v7
	s_waitcnt lgkmcnt(0)
	v_add_f32_e32 v2, v2, v8
	v_add_f32_e32 v2, v2, v9
	s_waitcnt vmcnt(0)
	v_lshlrev_b32_e32 v3, 16, v10
	v_add_f32_e32 v2, v2, v3
	v_mul_f32_e32 v3, v2, v2
	s_nop 1
	v_mov_b32_dpp v3, v3 quad_perm:[1,0,3,2] row_mask:0xf bank_mask:0xf bound_ctrl:1
	v_fmac_f32_e32 v3, v2, v2
	v_cvt_pk_bf16_f32 v2, v2, s0
	global_store_short v[0:1], v2, off
	v_add_f32_dpp v3, v3, v3 quad_perm:[2,3,0,1] row_mask:0xf bank_mask:0xf bound_ctrl:1
	s_nop 1
	v_add_f32_dpp v3, v3, v3 row_half_mirror row_mask:0xf bank_mask:0xf bound_ctrl:1
	s_nop 1
	v_add_f32_dpp v3, v3, v3 row_mirror row_mask:0xf bank_mask:0xf bound_ctrl:1
	ds_swizzle_b32 v4, v3 offset:swizzle(SWAP,16)
	s_waitcnt lgkmcnt(0)
	v_add_f32_e32 v0, v3, v4
	v_mov_b32_e32 v1, v0
	s_nop 1
	v_permlane32_swap_b32_e32 v0, v1
	s_and_saveexec_b64 s[42:43], vcc
	s_cbranch_execz .LBB0_1307
	s_lshl_b64 s[0:1], s[0:1], 6
	s_add_u32 s0, s18, s0
	v_add_f32_e32 v0, v0, v1
	s_addc_u32 s1, s38, s1
	global_store_dword v19, v0, s[0:1]
	s_branch .LBB0_1307

; #define LAS __attribute__((address_space(3)))
; __device__ __forceinline__ float bf1(bf16 b) { return __uint_as_float((unsigned)b << 16); }
; template <bool FIRST> __device__ __forceinline__ void skinny_resid(const bf16* __restrict__ A, const bf16* __restrict__ Bt, int K, const float* xs, bf16* XB, float* SS, int u, LAS unsigned char* lds, int tid) {
;     ...
;     const int lane = tid & 63, w = __builtin_amdgcn_readfirstlane(tid >> 6), r16 = lane & 15, kq = lane >> 4, rt = u & 7, cu = u >> 3;
;     const bf16* ap = A + (size_t)(NP + 16 * rt + r16) * K + 8 * kq + 32 * w;
;     const bf16* bp = Bt + (size_t)(64 * cu + r16) * K + 8 * kq + 32 * w;
;     f32x4v acc[4];
; #pragma unroll
;     for (int ct = 0; ct < 4; ++ct) acc[ct] = (f32x4v){0.f, 0.f, 0.f, 0.f};
;     const int nj = K / 256;
; #pragma unroll 1
;     for (int j0 = 0; j0 < nj; j0 += 4) { bf16x8 af[4], bf[4][4];
; #pragma unroll
;         for (int s = 0; s < 4; ++s) { const int j = (j0 + s < nj) ? j0 + s : nj - 1;
;             af[s] = *(const bf16x8*)(ap + 256 * j);
; #pragma unroll
;             for (int ct = 0; ct < 4; ++ct) bf[s][ct] = *(const bf16x8*)(bp + (size_t)16 * ct * K + 256 * j); }
;         __builtin_amdgcn_sched_barrier(0);
; #pragma unroll
;         for (int s = 0; s < 4; ++s) if (j0 + s < nj) {
; #pragma unroll
;             for (int ct = 0; ct < 4; ++ct) acc[ct] = __builtin_amdgcn_mfma_f32_16x16x32_bf16(af[s], bf[s][ct], acc[ct], 0, 0, 0); }
;         __builtin_amdgcn_sched_barrier(0); }
;     LAS float* red = (LAS float*)(lds + SK_RED);
; #pragma unroll
;     for (int ct = 0; ct < 4; ++ct) *(LAS f32x4v*)(red + ((w * 4 + ct) * 64 + lane) * 4) = acc[ct];
;     __syncthreads();
; #pragma unroll
;     for (int rr = 0; rr < 2; ++rr) { const int lr = 2 * w + rr;
;         const int ct = lane >> 4, src_lane = (lr >> 2) * 16 + (lane & 15), reg = lr & 3;
;         float s = 0.f;
; #pragma unroll
;         for (int ww = 0; ww < 8; ++ww) s += red[((ww * 4 + ct) * 64 + src_lane) * 4 + reg];
;         const int srow = 16 * rt + lr; const size_t row = (size_t)NP + srow; const int col = 64 * cu + lane;
;         const float x = (FIRST ? xs[(size_t)srow * D + col] : bf1(XB[row * D + col])) + s;
;         XB[row * D + col] = (bf16)(pk2(x, 0.f) & 0xffffu);
;         const float sq = wave_sum(x * x);
;         if (lane == 0) SS[row * 16 + cu] = sq; }
.LBB0_2980:
	v_mov_b32_e32 v5, v4
	s_ashr_i32 s6, s21, 3
	v_readfirstlane_b32 s7, v5
	v_and_b32_e32 v92, 15, v5
	s_and_b32 s24, s2, 0x70
	s_ashr_i32 s26, s7, 6
	v_or_b32_e32 v6, s24, v92
	s_lshl_b32 s22, s6, 6
	s_lshl_b32 s8, s26, 5
	v_or_b32_e32 v2, s22, v92
	v_lshlrev_b32_e32 v6, 11, v6
	v_mov_b32_e32 v7, v1
	s_ashr_i32 s9, s8, 31
	v_ashrrev_i32_e32 v3, 31, v2
	v_and_b32_e32 v0, 48, v5
	v_lshl_add_u64 v[6:7], s[16:17], 0, v[6:7]
	v_lshlrev_b64 v[2:3], 11, v[2:3]
	v_lshl_add_u64 v[6:7], v[6:7], 0, v[0:1]
	s_lshl_b64 s[8:9], s[8:9], 1
	v_lshl_add_u64 v[2:3], s[10:11], 0, v[2:3]
	v_lshl_add_u64 v[6:7], v[6:7], 0, s[8:9]
	v_lshl_add_u64 v[2:3], v[2:3], 0, v[0:1]
	v_add_co_u32_e32 v68, vcc, s5, v6
	v_lshl_add_u64 v[2:3], v[2:3], 0, s[8:9]
	s_nop 0
	v_addc_co_u32_e32 v69, vcc, 0, v7, vcc
	v_add_co_u32_e32 v86, vcc, s18, v2
	v_lshl_add_u64 v[66:67], v[6:7], 0, s[0:1]
	s_nop 0
	v_addc_co_u32_e32 v87, vcc, 0, v3, vcc
	v_add_co_u32_e32 v88, vcc, s19, v2
	s_nop 1
	v_addc_co_u32_e32 v89, vcc, 0, v3, vcc
	v_add_co_u32_e32 v90, vcc, s20, v2
	s_nop 1
	v_addc_co_u32_e32 v91, vcc, 0, v3, vcc
	global_load_dwordx4 v[6:9], v[86:87], off
	global_load_dwordx4 v[10:13], v[86:87], off offset:512
	global_load_dwordx4 v[14:17], v[88:89], off
	global_load_dwordx4 v[18:21], v[88:89], off offset:512
	global_load_dwordx4 v[22:25], v[90:91], off
	global_load_dwordx4 v[26:29], v[90:91], off offset:512
	global_load_dwordx4 v[30:33], v[66:67], off offset:512
	global_load_dwordx4 v[34:37], v[66:67], off offset:1024
	global_load_dwordx4 v[38:41], v[2:3], off offset:512
	global_load_dwordx4 v[42:45], v[2:3], off offset:1024
	global_load_dwordx4 v[46:49], v[2:3], off
	global_load_dwordx4 v[50:53], v[66:67], off offset:1536
	global_load_dwordx4 v[54:57], v[68:69], off
	global_load_dwordx4 v[58:61], v[2:3], off offset:1536
	global_load_dwordx4 v[62:65], v[86:87], off offset:1024
	s_nop 0
	global_load_dwordx4 v[66:69], v[86:87], off offset:1536
	global_load_dwordx4 v[70:73], v[88:89], off offset:1024
	global_load_dwordx4 v[74:77], v[88:89], off offset:1536
	global_load_dwordx4 v[78:81], v[90:91], off offset:1024
	global_load_dwordx4 v[82:85], v[90:91], off offset:1536
	v_and_b32_e32 v86, 63, v5
	s_waitcnt vmcnt(7)
	v_mfma_f32_16x16x32_bf16 v[6:9], v[54:57], v[6:9], 0
	v_mfma_f32_16x16x32_bf16 v[46:49], v[54:57], v[46:49], 0
	v_mfma_f32_16x16x32_bf16 v[14:17], v[54:57], v[14:17], 0
	v_mfma_f32_16x16x32_bf16 v[22:25], v[54:57], v[22:25], 0
	v_mfma_f32_16x16x32_bf16 v[6:9], v[30:33], v[10:13], v[6:9]
	v_mfma_f32_16x16x32_bf16 v[38:41], v[30:33], v[38:41], v[46:49]
	v_mfma_f32_16x16x32_bf16 v[10:13], v[30:33], v[18:21], v[14:17]
	v_mfma_f32_16x16x32_bf16 v[14:17], v[30:33], v[26:29], v[22:25]
	s_waitcnt vmcnt(5)
	v_mfma_f32_16x16x32_bf16 v[6:9], v[34:37], v[62:65], v[6:9]
	v_mfma_f32_16x16x32_bf16 v[18:21], v[34:37], v[42:45], v[38:41]
	s_waitcnt vmcnt(3)
	v_mfma_f32_16x16x32_bf16 v[10:13], v[34:37], v[70:73], v[10:13]
	s_waitcnt vmcnt(1)
	v_mfma_f32_16x16x32_bf16 v[14:17], v[34:37], v[78:81], v[14:17]
	v_mfma_f32_16x16x32_bf16 v[6:9], v[50:53], v[66:69], v[6:9]
	v_mfma_f32_16x16x32_bf16 v[18:21], v[50:53], v[58:61], v[18:21]
	v_mfma_f32_16x16x32_bf16 v[10:13], v[50:53], v[74:77], v[10:13]
	s_waitcnt vmcnt(0)
	v_mfma_f32_16x16x32_bf16 v[14:17], v[50:53], v[82:85], v[14:17]
	s_lshr_b32 s7, s7, 3
	s_lshl_b32 s8, s26, 12
	s_and_b32 s27, s7, 0xffffff0
	s_ashr_i32 s7, s6, 31
	s_add_i32 s8, s8, 0
	s_lshl_b32 s25, s26, 1
	s_bitset1_b32 s24, 14
	s_lshl_b64 s[6:7], s[6:7], 2
	v_or_b32_e32 v2, s22, v86
	s_add_u32 s22, s12, s6
	s_addc_u32 s23, s13, s7
	s_add_i32 s6, s25, s24
	v_ashrrev_i32_e32 v3, 31, v2
	s_ashr_i32 s7, s6, 31
	v_lshl_add_u32 v0, v86, 4, s8
	v_lshl_add_u64 v[2:3], v[2:3], 1, s[14:15]
	s_lshl_b64 s[8:9], s[6:7], 11
	ds_write_b128 v0, v[18:21]
	ds_write_b128 v0, v[6:9] offset:1024
	ds_write_b128 v0, v[10:13] offset:2048
	ds_write_b128 v0, v[14:17] offset:3072
	v_lshl_add_u64 v[6:7], v[2:3], 0, s[8:9]
	s_waitcnt lgkmcnt(0)
	s_barrier
	global_load_ushort v16, v[6:7], off
	s_or_b32 s98, s25, 1
	s_add_i32 s98, s98, s24
	s_ashr_i32 s99, s98, 31
	s_lshl_b64 s[98:99], s[98:99], 11
	v_lshl_add_u64 v[240:241], v[2:3], 0, s[98:99]
	global_load_ushort v242, v[240:241], off
	s_lshl_b32 s8, s26, 3
	v_lshlrev_b32_e32 v0, 6, v5
	v_or_b32_e32 v5, s27, v92
	s_and_b32 s8, s8, 8
	v_and_b32_e32 v0, 0xc00, v0
	v_lshlrev_b32_e32 v5, 4, v5
	s_add_i32 s8, s8, 0
	v_add3_u32 v14, s8, v0, v5
	ds_read2st64_b32 v[8:9], v14 offset1:16
	ds_read2st64_b32 v[10:11], v14 offset0:32 offset1:48
	ds_read2st64_b32 v[12:13], v14 offset0:64 offset1:80
	ds_read2st64_b32 v[14:15], v14 offset0:96 offset1:112
	v_cmp_eq_u32_e32 vcc, 0, v86
	s_waitcnt lgkmcnt(3)
	v_add_f32_e32 v8, 0, v8
	v_add_f32_e32 v8, v8, v9
	s_waitcnt lgkmcnt(2)
	v_add_f32_e32 v8, v8, v10
	v_add_f32_e32 v8, v8, v11
	s_waitcnt lgkmcnt(1)
	v_add_f32_e32 v8, v8, v12
	v_add_f32_e32 v8, v8, v13
	s_waitcnt lgkmcnt(0)
	v_add_f32_e32 v8, v8, v14
	v_add_f32_e32 v8, v8, v15
	s_waitcnt vmcnt(0)
	v_lshlrev_b32_e32 v9, 16, v16
	v_add_f32_e32 v8, v8, v9
	v_mul_f32_e32 v9, v8, v8
	s_nop 1
	v_mov_b32_dpp v9, v9 quad_perm:[1,0,3,2] row_mask:0xf bank_mask:0xf bound_ctrl:1
	v_fmac_f32_e32 v9, v8, v8
	v_cvt_pk_bf16_f32 v8, v8, s0
	global_store_short v[6:7], v8, off
	v_add_f32_dpp v9, v9, v9 quad_perm:[2,3,0,1] row_mask:0xf bank_mask:0xf bound_ctrl:1
	s_nop 1
	v_add_f32_dpp v9, v9, v9 row_half_mirror row_mask:0xf bank_mask:0xf bound_ctrl:1
	s_nop 1
	v_add_f32_dpp v9, v9, v9 row_mirror row_mask:0xf bank_mask:0xf bound_ctrl:1
	ds_swizzle_b32 v10, v9 offset:swizzle(SWAP,16)
	s_waitcnt lgkmcnt(0)
	v_add_f32_e32 v6, v9, v10
	v_mov_b32_e32 v7, v6
	s_nop 1
	v_permlane32_swap_b32_e32 v6, v7
	s_and_saveexec_b64 s[8:9], vcc
	s_cbranch_execz .LBB0_2982
	s_lshl_b64 s[6:7], s[6:7], 6
	s_add_u32 s6, s22, s6
	v_add_f32_e32 v6, v6, v7
	s_addc_u32 s7, s23, s7
	global_store_dword v1, v6, s[6:7]
; __device__ __forceinline__ unsigned pk2(float lo, float hi) { f32x2_t v = {lo, hi}; bf16x2_t b = __builtin_convertvector(v, bf16x2_t); return __builtin_bit_cast(unsigned, b); }
; __device__ __forceinline__ float bf1(bf16 b) { return __uint_as_float((unsigned)b << 16); }
; __device__ __forceinline__ float wave_sum(float v) { v = sum16(v); v += lane_xor<16>(v); return xhalf_sum(v); }
; template <bool FIRST> __device__ __forceinline__ void skinny_resid(const bf16* __restrict__ A, const bf16* __restrict__ Bt, int K, const float* xs, bf16* XB, float* SS, int u, LAS unsigned char* lds, int tid) {
;     ...
;     for (int rr = 0; rr < 2; ++rr) { const int lr = 2 * w + rr;
;         const int ct = lane >> 4, src_lane = (lr >> 2) * 16 + (lane & 15), reg = lr & 3;
;         float s = 0.f;
; #pragma unroll
;         for (int ww = 0; ww < 8; ++ww) s += red[((ww * 4 + ct) * 64 + src_lane) * 4 + reg];
;         const int srow = 16 * rt + lr; const size_t row = (size_t)NP + srow; const int col = 64 * cu + lane;
;         const float x = (FIRST ? xs[(size_t)srow * D + col] : bf1(XB[row * D + col])) + s;
;         XB[row * D + col] = (bf16)(pk2(x, 0.f) & 0xffffu);
;         const float sq = wave_sum(x * x);
;         if (lane == 0) SS[row * 16 + cu] = sq; }
.LBB0_2982:
	s_or_b64 exec, exec, s[8:9]
	s_or_b32 s25, s25, 1
	s_add_i32 s6, s25, s24
	s_ashr_i32 s7, s6, 31
	s_lshl_b64 s[8:9], s[6:7], 11
	v_lshl_add_u64 v[2:3], v[2:3], 0, s[8:9]
	v_mov_b32_e32 v14, v242
	s_and_b32 s8, s25, 3
	s_lshl_b32 s8, s8, 2
	s_add_i32 s8, s8, 0
	v_add3_u32 v0, s8, v0, v5
	ds_read2st64_b32 v[6:7], v0 offset1:16
	ds_read2st64_b32 v[8:9], v0 offset0:32 offset1:48
	ds_read2st64_b32 v[10:11], v0 offset0:64 offset1:80
	ds_read2st64_b32 v[12:13], v0 offset0:96 offset1:112
	s_waitcnt lgkmcnt(3)
	v_add_f32_e32 v0, 0, v6
	v_add_f32_e32 v0, v0, v7
	s_waitcnt lgkmcnt(2)
	v_add_f32_e32 v0, v0, v8
	v_add_f32_e32 v0, v0, v9
	s_waitcnt lgkmcnt(1)
	v_add_f32_e32 v0, v0, v10
	v_add_f32_e32 v0, v0, v11
	s_waitcnt lgkmcnt(0)
	v_add_f32_e32 v0, v0, v12
	v_add_f32_e32 v0, v0, v13
	s_waitcnt vmcnt(0)
	v_lshlrev_b32_e32 v5, 16, v14
	v_add_f32_e32 v0, v0, v5
	v_mul_f32_e32 v5, v0, v0
	s_nop 1
	v_mov_b32_dpp v5, v5 quad_perm:[1,0,3,2] row_mask:0xf bank_mask:0xf bound_ctrl:1
	v_fmac_f32_e32 v5, v0, v0
	v_cvt_pk_bf16_f32 v0, v0, s0
	global_store_short v[2:3], v0, off
	v_add_f32_dpp v5, v5, v5 quad_perm:[2,3,0,1] row_mask:0xf bank_mask:0xf bound_ctrl:1
	s_nop 1
	v_add_f32_dpp v5, v5, v5 row_half_mirror row_mask:0xf bank_mask:0xf bound_ctrl:1
	s_nop 1
	v_add_f32_dpp v5, v5, v5 row_mirror row_mask:0xf bank_mask:0xf bound_ctrl:1
	ds_swizzle_b32 v6, v5 offset:swizzle(SWAP,16)
	s_waitcnt lgkmcnt(0)
	v_add_f32_e32 v0, v5, v6
	v_mov_b32_e32 v2, v0
	s_nop 1
	v_permlane32_swap_b32_e32 v0, v2
	s_and_saveexec_b64 s[8:9], vcc
	s_cbranch_execz .LBB0_2979
	s_lshl_b64 s[6:7], s[6:7], 6
	s_add_u32 s6, s22, s6
	v_add_f32_e32 v0, v0, v2
	s_addc_u32 s7, s23, s7
	global_store_dword v1, v0, s[6:7]
	s_branch .LBB0_2979

; #define LAS __attribute__((address_space(3)))
; __device__ __forceinline__ unsigned pk2(float lo, float hi) { f32x2_t v = {lo, hi}; bf16x2_t b = __builtin_convertvector(v, bf16x2_t); return __builtin_bit_cast(unsigned, b); }
; __device__ __forceinline__ float bf1(bf16 b) { return __uint_as_float((unsigned)b << 16); }
; __device__ __forceinline__ float wave_sum(float v) { v = sum16(v); v += lane_xor<16>(v); return xhalf_sum(v); }
; template <bool FIRST> __device__ __forceinline__ void skinny_resid(const bf16* __restrict__ A, const bf16* __restrict__ Bt, int K, const float* xs, bf16* XB, float* SS, int u, LAS unsigned char* lds, int tid) {
;     ...
;     LAS float* red = (LAS float*)(lds + SK_RED);
; #pragma unroll
;     for (int ct = 0; ct < 4; ++ct) *(LAS f32x4v*)(red + ((w * 4 + ct) * 64 + lane) * 4) = acc[ct];
;     __syncthreads();
; #pragma unroll
;     for (int rr = 0; rr < 2; ++rr) { const int lr = 2 * w + rr;
;         const int ct = lane >> 4, src_lane = (lr >> 2) * 16 + (lane & 15), reg = lr & 3;
;         float s = 0.f;
; #pragma unroll
;         for (int ww = 0; ww < 8; ++ww) s += red[((ww * 4 + ct) * 64 + src_lane) * 4 + reg];
;         const int srow = 16 * rt + lr; const size_t row = (size_t)NP + srow; const int col = 64 * cu + lane;
;         const float x = (FIRST ? xs[(size_t)srow * D + col] : bf1(XB[row * D + col])) + s;
;         XB[row * D + col] = (bf16)(pk2(x, 0.f) & 0xffffu);
;         const float sq = wave_sum(x * x);
;         if (lane == 0) SS[row * 16 + cu] = sq; }
.LBB0_3165:
	s_lshr_b32 s1, s1, 3
	s_lshl_b32 s6, s10, 12
	s_and_b32 s30, s1, 0xffffff0
	s_ashr_i32 s1, s0, 31
	s_add_i32 s6, s6, 0
	s_lshl_b32 s27, s10, 1
	s_or_b32 s26, s11, 0x4000
	s_lshl_b64 s[0:1], s[0:1], 2
	v_lshl_add_u32 v18, v31, 4, s6
	s_add_u32 s6, s14, s0
	ds_write_b128 v18, v[12:15]
	ds_write_b128 v18, v[8:11] offset:1024
	ds_write_b128 v18, v[4:7] offset:2048
	ds_write_b128 v18, v[0:3] offset:3072
	v_or_b32_e32 v0, s25, v31
	s_addc_u32 s25, s15, s1
	s_add_i32 s0, s27, s26
	v_ashrrev_i32_e32 v1, 31, v0
	s_ashr_i32 s1, s0, 31
	v_lshl_add_u64 v[0:1], v[0:1], 1, s[16:17]
	s_lshl_b64 s[28:29], s[0:1], 11
	v_lshl_add_u64 v[4:5], v[0:1], 0, s[28:29]
	s_waitcnt lgkmcnt(0)
	s_barrier
	global_load_ushort v14, v[4:5], off
	s_or_b32 s98, s27, 1
	s_add_i32 s98, s98, s26
	s_ashr_i32 s99, s98, 31
	s_lshl_b64 s[98:99], s[98:99], 11
	v_lshl_add_u64 v[240:241], v[0:1], 0, s[98:99]
	global_load_ushort v242, v[240:241], off
	s_lshl_b32 s10, s10, 3
	v_or_b32_e32 v3, s30, v32
	s_and_b32 s10, s10, 8
	v_lshlrev_b32_e32 v2, 10, v33
	v_lshlrev_b32_e32 v3, 4, v3
	s_add_i32 s10, s10, 0
	v_add3_u32 v12, s10, v2, v3
	ds_read2st64_b32 v[6:7], v12 offset1:16
	ds_read2st64_b32 v[8:9], v12 offset0:32 offset1:48
	ds_read2st64_b32 v[10:11], v12 offset0:64 offset1:80
	ds_read2st64_b32 v[12:13], v12 offset0:96 offset1:112
	v_cmp_eq_u32_e32 vcc, 0, v31
	s_waitcnt lgkmcnt(3)
	v_add_f32_e32 v6, 0, v6
	v_add_f32_e32 v6, v6, v7
	s_waitcnt lgkmcnt(2)
	v_add_f32_e32 v6, v6, v8
	v_add_f32_e32 v6, v6, v9
	s_waitcnt lgkmcnt(1)
	v_add_f32_e32 v6, v6, v10
	v_add_f32_e32 v6, v6, v11
	s_waitcnt lgkmcnt(0)
	v_add_f32_e32 v6, v6, v12
	v_add_f32_e32 v6, v6, v13
	s_waitcnt vmcnt(0)
	v_lshlrev_b32_e32 v7, 16, v14
	v_add_f32_e32 v6, v6, v7
	v_mul_f32_e32 v7, v6, v6
	s_nop 1
	v_mov_b32_dpp v7, v7 quad_perm:[1,0,3,2] row_mask:0xf bank_mask:0xf bound_ctrl:1
	v_fmac_f32_e32 v7, v6, v6
	v_cvt_pk_bf16_f32 v6, v6, s0
	global_store_short v[4:5], v6, off
	v_add_f32_dpp v7, v7, v7 quad_perm:[2,3,0,1] row_mask:0xf bank_mask:0xf bound_ctrl:1
	s_nop 1
	v_add_f32_dpp v7, v7, v7 row_half_mirror row_mask:0xf bank_mask:0xf bound_ctrl:1
	s_nop 1
	v_add_f32_dpp v7, v7, v7 row_mirror row_mask:0xf bank_mask:0xf bound_ctrl:1
	ds_swizzle_b32 v8, v7 offset:swizzle(SWAP,16)
	s_waitcnt lgkmcnt(0)
	v_add_f32_e32 v4, v7, v8
	v_mov_b32_e32 v5, v4
	s_nop 1
	v_permlane32_swap_b32_e32 v4, v5
	s_and_saveexec_b64 s[10:11], vcc
	s_cbranch_execz .LBB0_3167
	s_lshl_b64 s[0:1], s[0:1], 6
	s_add_u32 s0, s6, s0
	v_add_f32_e32 v4, v4, v5
	s_addc_u32 s1, s25, s1
	global_store_dword v19, v4, s[0:1]
.LBB0_3167:
	s_or_b64 exec, exec, s[10:11]
	s_or_b32 s27, s27, 1
	s_add_i32 s0, s27, s26
	s_ashr_i32 s1, s0, 31
	s_lshl_b64 s[10:11], s[0:1], 11
	v_lshl_add_u64 v[0:1], v[0:1], 0, s[10:11]
	v_mov_b32_e32 v10, v242
	s_and_b32 s10, s27, 3
	s_lshl_b32 s10, s10, 2
	s_add_i32 s10, s10, 0
	v_add3_u32 v8, s10, v2, v3
	ds_read2st64_b32 v[2:3], v8 offset1:16
	ds_read2st64_b32 v[4:5], v8 offset0:32 offset1:48
	ds_read2st64_b32 v[6:7], v8 offset0:64 offset1:80
	ds_read2st64_b32 v[8:9], v8 offset0:96 offset1:112
	s_waitcnt lgkmcnt(3)
	v_add_f32_e32 v2, 0, v2
	v_add_f32_e32 v2, v2, v3
	s_waitcnt lgkmcnt(2)
	v_add_f32_e32 v2, v2, v4
	v_add_f32_e32 v2, v2, v5
	s_waitcnt lgkmcnt(1)
	v_add_f32_e32 v2, v2, v6
	v_add_f32_e32 v2, v2, v7
	s_waitcnt lgkmcnt(0)
	v_add_f32_e32 v2, v2, v8
	v_add_f32_e32 v2, v2, v9
	s_waitcnt vmcnt(0)
	v_lshlrev_b32_e32 v3, 16, v10
	v_add_f32_e32 v2, v2, v3
	v_mul_f32_e32 v3, v2, v2
	s_nop 1
	v_mov_b32_dpp v3, v3 quad_perm:[1,0,3,2] row_mask:0xf bank_mask:0xf bound_ctrl:1
	v_fmac_f32_e32 v3, v2, v2
	v_cvt_pk_bf16_f32 v2, v2, s0
	global_store_short v[0:1], v2, off
	v_add_f32_dpp v3, v3, v3 quad_perm:[2,3,0,1] row_mask:0xf bank_mask:0xf bound_ctrl:1
	s_nop 1
	v_add_f32_dpp v3, v3, v3 row_half_mirror row_mask:0xf bank_mask:0xf bound_ctrl:1
	s_nop 1
	v_add_f32_dpp v3, v3, v3 row_mirror row_mask:0xf bank_mask:0xf bound_ctrl:1
	ds_swizzle_b32 v4, v3 offset:swizzle(SWAP,16)
	s_waitcnt lgkmcnt(0)
	v_add_f32_e32 v0, v3, v4
	v_mov_b32_e32 v1, v0
	s_nop 1
	v_permlane32_swap_b32_e32 v0, v1
	s_and_saveexec_b64 s[10:11], vcc
	s_cbranch_execz .LBB0_3160
	s_lshl_b64 s[0:1], s[0:1], 6
	s_add_u32 s0, s6, s0
	v_add_f32_e32 v0, v0, v1
	s_addc_u32 s1, s25, s1
	global_store_dword v19, v0, s[0:1]
	s_branch .LBB0_3160

; __global__ void __launch_bounds__(NWAVES * 64, 2) nsa_fwd(Args args) {
	.amdhsa_kernel _Z7nsa_fwd4Args
		.amdhsa_group_segment_fixed_size 0
		.amdhsa_private_segment_fixed_size 0
		.amdhsa_kernarg_size 440
		.amdhsa_user_sgpr_count 2
		.amdhsa_user_sgpr_dispatch_ptr 0
		.amdhsa_user_sgpr_queue_ptr 0
		.amdhsa_user_sgpr_kernarg_segment_ptr 1
		.amdhsa_user_sgpr_dispatch_id 0
		.amdhsa_user_sgpr_kernarg_preload_length 0
		.amdhsa_user_sgpr_kernarg_preload_offset 0
		.amdhsa_user_sgpr_private_segment_size 0
		.amdhsa_uses_dynamic_stack 0
		.amdhsa_enable_private_segment 0
		.amdhsa_system_sgpr_workgroup_id_x 1
		.amdhsa_system_sgpr_workgroup_id_y 0
		.amdhsa_system_sgpr_workgroup_id_z 0
		.amdhsa_system_sgpr_workgroup_info 0
		.amdhsa_system_vgpr_workitem_id 0
		.amdhsa_next_free_vgpr 255
		.amdhsa_next_free_sgpr 102
		.amdhsa_accum_offset 256
		.amdhsa_reserve_vcc 1
		.amdhsa_float_round_mode_32 0
		.amdhsa_float_round_mode_16_64 0
		.amdhsa_float_denorm_mode_32 3
		.amdhsa_float_denorm_mode_16_64 3
		.amdhsa_dx10_clamp 1
		.amdhsa_ieee_mode 1
		.amdhsa_fp16_overflow 0
		.amdhsa_tg_split 0
		.amdhsa_exception_fp_ieee_invalid_op 0
		.amdhsa_exception_fp_denorm_src 0
		.amdhsa_exception_fp_ieee_div_zero 0
		.amdhsa_exception_fp_ieee_overflow 0
		.amdhsa_exception_fp_ieee_underflow 0
		.amdhsa_exception_fp_ieee_inexact 0
		.amdhsa_exception_int_div_zero 0
	.end_amdhsa_kernel

; __global__ void __launch_bounds__(NWAVES * 64, 2) nsa_fwd(Args args) {
amdhsa.kernels:
  - .agpr_count:     0
    .args:
      - .offset:         0
        .size:           184
        .value_kind:     by_value
      - .offset:         184
        .size:           4
        .value_kind:     hidden_block_count_x
      - .offset:         188
        .size:           4
        .value_kind:     hidden_block_count_y
      - .offset:         192
        .size:           4
        .value_kind:     hidden_block_count_z
      - .offset:         196
        .size:           2
        .value_kind:     hidden_group_size_x
      - .offset:         198
        .size:           2
        .value_kind:     hidden_group_size_y
      - .offset:         200
        .size:           2
        .value_kind:     hidden_group_size_z
      - .offset:         202
        .size:           2
        .value_kind:     hidden_remainder_x
      - .offset:         204
        .size:           2
        .value_kind:     hidden_remainder_y
      - .offset:         206
        .size:           2
        .value_kind:     hidden_remainder_z
      - .offset:         224
        .size:           8
        .value_kind:     hidden_global_offset_x
      - .offset:         232
        .size:           8
        .value_kind:     hidden_global_offset_y
      - .offset:         240
        .size:           8
        .value_kind:     hidden_global_offset_z
      - .offset:         248
        .size:           2
        .value_kind:     hidden_grid_dims
      - .offset:         304
        .size:           4
        .value_kind:     hidden_dynamic_lds_size
    .group_segment_fixed_size: 0
    .kernarg_segment_align: 8
    .kernarg_segment_size: 440
    .language:       OpenCL C
    .language_version:
      - 2
      - 0
    .max_flat_workgroup_size: 512
    .name:           _Z7nsa_fwd4Args
    .private_segment_fixed_size: 0
    .sgpr_count:     108
    .sgpr_spill_count: 80
    .symbol:         _Z7nsa_fwd4Args.kd
    .uniform_work_group_size: 1
    .uses_dynamic_stack: false
    .vgpr_count:     255
    .vgpr_spill_count: 0
    .wavefront_size: 64
